# P6 residual epilogue: per-half-group vmcnt(0) waits (which waited for the previous group's stores) moved into the layer-0 f32-base path only
# speedup vs baseline: 1.0271x; 1.0045x over previous
;     __device__ __forceinline__ void operator()(const f32x4 (&acc)[2][2][4][2], const Unit& u, int wr, int wc, int fr, int fq) const {
;     ...
;         for (int ai = 0; ai < 2; ++ai)
; #pragma unroll
;             for (int m = 0; m < 4; ++m) {
;                 const int row = row0 + ai * 128 + m * 16; const size_t off = (size_t)row * DM + col0; float ss = 0.f;
; #pragma unroll
;                 for (int bj = 0; bj < 2; ++bj) {
;                     f32x4 b0, b1;
;                     if (base32) { b0 = __builtin_nontemporal_load((const f32x4*)(base32 + off + bj * 128)); b1 = __builtin_nontemporal_load((const f32x4*)(base32 + off + bj * 128 + 4)); }
;                     else { const u32x4 w = bw[ai][m][bj]; b0 = (f32x4){bflo(w.x), bfhi(w.x), bflo(w.y), bfhi(w.y)}; b1 = (f32x4){bflo(w.z), bfhi(w.z), bflo(w.w), bfhi(w.w)}; }
;                     const f32x4 x0 = b0 + acc[ai][bj][m][0], x1 = b1 + acc[ai][bj][m][1];
.LBB0_705:
	v_lshlrev_b64 v[192:193], 10, v[222:223]
	v_lshl_add_u64 v[234:235], v[192:193], 0, v[224:225]
	s_and_b64 vcc, exec, s[44:45]
	v_lshl_add_u64 v[232:233], v[234:235], 2, s[20:21]
	s_cbranch_vccnz .LBB0_772
	global_load_dwordx4 v[196:199], v[232:233], off offset:16 nt
	global_load_dwordx4 v[192:195], v[232:233], off nt
	s_waitcnt vmcnt(0)
	s_cbranch_execnz .LBB0_708

; __device__ __forceinline__ u32x4 pack8(f32x4 v0, f32x4 v1) { u32x4 w; w.x = pk2(v0[0], v0[1]); w.y = pk2(v0[2], v0[3]); w.z = pk2(v1[0], v1[1]); w.w = pk2(v1[2], v1[3]); return w; }
;     __device__ __forceinline__ void operator()(const f32x4 (&acc)[2][2][4][2], const Unit& u, int wr, int wc, int fr, int fq) const {
;     ...
;         for (int ai = 0; ai < 2; ++ai)
; #pragma unroll
;             for (int m = 0; m < 4; ++m) {
;                 const int row = row0 + ai * 128 + m * 16; const size_t off = (size_t)row * DM + col0; float ss = 0.f;
; #pragma unroll
;                 for (int bj = 0; bj < 2; ++bj) {
;                     f32x4 b0, b1;
;                     if (base32) { b0 = __builtin_nontemporal_load((const f32x4*)(base32 + off + bj * 128)); b1 = __builtin_nontemporal_load((const f32x4*)(base32 + off + bj * 128 + 4)); }
;                     else { const u32x4 w = bw[ai][m][bj]; b0 = (f32x4){bflo(w.x), bfhi(w.x), bflo(w.y), bfhi(w.y)}; b1 = (f32x4){bflo(w.z), bfhi(w.z), bflo(w.w), bfhi(w.w)}; }
;                     const f32x4 x0 = b0 + acc[ai][bj][m][0], x1 = b1 + acc[ai][bj][m][1];
;                     if (out32) { __builtin_nontemporal_store(x0, (f32x4*)(out32 + off + bj * 128)); __builtin_nontemporal_store(x1, (f32x4*)(out32 + off + bj * 128 + 4)); }
;                     else *(u32x4*)(XN + off + bj * 128) = pack8(x0, x1);
;                     ss += ((x0[0] * x0[0] + x0[1] * x0[1]) + (x0[2] * x0[2] + x0[3] * x0[3])) + ((x1[0] * x1[0] + x1[1] * x1[1]) + (x1[2] * x1[2] + x1[3] * x1[3]));
;                 }
;                 ss += __shfl_xor(ss, 16); ss += __shfl_xor(ss, 32);
;                 if (fq == 0) part[(size_t)row * 16 + u.pn * 4 + wc] = ss;
;             }
.LBB0_708:
	s_waitcnt lgkmcnt(0)
	v_pk_add_f32 v[190:191], v[158:159], v[194:195]
	v_pk_add_f32 v[194:195], v[156:157], v[192:193]
	v_pk_add_f32 v[192:193], v[154:155], v[198:199]
	v_pk_add_f32 v[196:197], v[152:153], v[196:197]
	v_cvt_pk_bf16_f32 v152, v194, v195
	v_cvt_pk_bf16_f32 v153, v190, v191
	v_cvt_pk_bf16_f32 v154, v196, v197
	v_cvt_pk_bf16_f32 v155, v192, v193
	v_lshl_add_u64 v[188:189], v[234:235], 1, s[54:55]
	s_and_b64 vcc, exec, s[44:45]
	flat_store_dwordx4 v[188:189], v[152:155]
	s_cbranch_vccnz .LBB0_773
	global_load_dwordx4 v[156:159], v[232:233], off offset:528 nt
	global_load_dwordx4 v[152:155], v[232:233], off offset:512 nt
	s_waitcnt vmcnt(0)
	s_cbranch_execnz .LBB0_711
.LBB0_710:
	s_nop 0
	v_lshlrev_b32_e32 v152, 16, v184
	v_and_b32_e32 v153, 0xffff0000, v184
	v_lshlrev_b32_e32 v154, 16, v185
	v_and_b32_e32 v155, 0xffff0000, v185
	v_lshlrev_b32_e32 v156, 16, v186
	v_and_b32_e32 v157, 0xffff0000, v186
	v_lshlrev_b32_e32 v158, 16, v187
	v_and_b32_e32 v159, 0xffff0000, v187
.LBB0_711:
	v_mul_f32_e32 v184, v195, v195
	v_mul_f32_e32 v185, v191, v191
	v_fmac_f32_e32 v184, v194, v194
	v_fmac_f32_e32 v185, v190, v190
	v_pk_add_f32 v[146:147], v[146:147], v[154:155]
	v_pk_add_f32 v[144:145], v[144:145], v[152:153]
	v_add_f32_e32 v184, v184, v185
	v_mul_f32_e32 v185, v197, v197
	v_mul_f32_e32 v186, v193, v193
	v_pk_add_f32 v[154:155], v[140:141], v[156:157]
	v_mul_f32_e32 v140, v145, v145
	v_mul_f32_e32 v141, v147, v147
	v_fmac_f32_e32 v185, v196, v196
	v_fmac_f32_e32 v186, v192, v192
	v_pk_add_f32 v[152:153], v[142:143], v[158:159]
	v_fmac_f32_e32 v140, v144, v144
	v_fmac_f32_e32 v141, v146, v146
	v_add_f32_e32 v185, v185, v186
	v_and_b32_e32 v186, 64, v243
	v_add_f32_e32 v140, v140, v141
	v_mul_f32_e32 v141, v155, v155
	v_mul_f32_e32 v142, v153, v153
	v_add_f32_e32 v185, v184, v185
	v_xor_b32_e32 v184, 16, v243
	v_add_u32_e32 v186, 64, v186
	v_fmac_f32_e32 v141, v154, v154
	v_fmac_f32_e32 v142, v152, v152
	v_cmp_lt_i32_e32 vcc, v184, v186
	v_add_f32_e32 v141, v141, v142
	v_add_f32_e32 v140, v140, v141
	v_cndmask_b32_e32 v184, v243, v184, vcc
	v_lshlrev_b32_e32 v184, 2, v184
	v_add_f32_e32 v140, v185, v140
	ds_bpermute_b32 v141, v184, v140
	v_xor_b32_e32 v187, 32, v243
	v_cmp_lt_i32_e32 vcc, v187, v186
	s_lshl_b32 s92, s92, 2
	s_ashr_i32 s93, s92, 31
	v_cndmask_b32_e32 v186, v243, v187, vcc
	v_lshlrev_b32_e32 v158, 2, v186
	s_waitcnt lgkmcnt(0)
	v_add_f32_e32 v140, v140, v141
	ds_bpermute_b32 v141, v158, v140
	v_cvt_pk_bf16_f32 v142, v144, v145
	v_cvt_pk_bf16_f32 v143, v146, v147
	v_cvt_pk_bf16_f32 v144, v154, v155
	v_cvt_pk_bf16_f32 v145, v152, v153
	flat_store_dwordx4 v[188:189], v[142:145] offset:256
	s_and_saveexec_b64 s[30:31], s[40:41]
	s_cbranch_execz .LBB0_713
	v_lshlrev_b64 v[142:143], 6, v[222:223]
	v_lshl_add_u64 v[142:143], s[62:63], 0, v[142:143]
	v_lshl_add_u64 v[142:143], s[92:93], 2, v[142:143]
	s_lshl_b32 s58, s53, 2
	v_lshl_add_u64 v[142:143], v[142:143], 0, s[58:59]
	s_waitcnt lgkmcnt(0)
	v_add_f32_e32 v140, v140, v141
	flat_store_dword v[142:143], v140
.LBB0_713:
	s_or_b64 exec, exec, s[30:31]
	s_waitcnt lgkmcnt(0)
	v_lshlrev_b64 v[140:141], 10, v[230:231]
	v_lshl_add_u64 v[154:155], v[140:141], 0, v[224:225]
	s_and_b64 vcc, exec, s[44:45]
	v_lshl_add_u64 v[152:153], v[154:155], 2, s[20:21]
	s_cbranch_vccnz .LBB0_774
	global_load_dwordx4 v[144:147], v[152:153], off offset:16 nt
	global_load_dwordx4 v[140:143], v[152:153], off nt
	s_waitcnt vmcnt(0)
	s_cbranch_execnz .LBB0_716
.LBB0_715:
	s_nop 0
	v_lshlrev_b32_e32 v140, 16, v180
	v_and_b32_e32 v141, 0xffff0000, v180
	v_lshlrev_b32_e32 v142, 16, v181
	v_and_b32_e32 v143, 0xffff0000, v181
	v_lshlrev_b32_e32 v144, 16, v182
	v_and_b32_e32 v145, 0xffff0000, v182
	v_lshlrev_b32_e32 v146, 16, v183
	v_and_b32_e32 v147, 0xffff0000, v183
.LBB0_716:
	v_pk_add_f32 v[142:143], v[134:135], v[142:143]
	v_pk_add_f32 v[156:157], v[132:133], v[140:141]
	v_pk_add_f32 v[146:147], v[130:131], v[146:147]
	v_pk_add_f32 v[144:145], v[128:129], v[144:145]
	v_cvt_pk_bf16_f32 v128, v156, v157
	v_cvt_pk_bf16_f32 v129, v142, v143
	v_cvt_pk_bf16_f32 v130, v144, v145
	v_cvt_pk_bf16_f32 v131, v146, v147
	v_lshl_add_u64 v[140:141], v[154:155], 1, s[54:55]
	s_and_b64 vcc, exec, s[44:45]
	flat_store_dwordx4 v[140:141], v[128:131]
	s_cbranch_vccnz .LBB0_775
	global_load_dwordx4 v[132:135], v[152:153], off offset:528 nt
	global_load_dwordx4 v[128:131], v[152:153], off offset:512 nt
	s_waitcnt vmcnt(0)
	s_cbranch_execnz .LBB0_719
.LBB0_718:
	s_nop 0
	v_lshlrev_b32_e32 v128, 16, v176
	v_and_b32_e32 v129, 0xffff0000, v176
	v_lshlrev_b32_e32 v130, 16, v177
	v_and_b32_e32 v131, 0xffff0000, v177
	v_lshlrev_b32_e32 v132, 16, v178
	v_and_b32_e32 v133, 0xffff0000, v178
	v_lshlrev_b32_e32 v134, 16, v179
	v_and_b32_e32 v135, 0xffff0000, v179
.LBB0_719:
	v_mul_f32_e32 v152, v157, v157
	v_mul_f32_e32 v143, v143, v143
	v_pk_add_f32 v[122:123], v[122:123], v[130:131]
	v_pk_add_f32 v[120:121], v[120:121], v[128:129]
	v_fmac_f32_e32 v152, v156, v156
	v_fmac_f32_e32 v143, v142, v142
	v_pk_add_f32 v[130:131], v[116:117], v[132:133]
	v_mul_f32_e32 v116, v121, v121
	v_mul_f32_e32 v117, v123, v123
	v_add_f32_e32 v142, v152, v143
	v_mul_f32_e32 v143, v145, v145
	v_pk_add_f32 v[128:129], v[118:119], v[134:135]
	v_fmac_f32_e32 v116, v120, v120
	v_fmac_f32_e32 v117, v122, v122
	v_fmac_f32_e32 v143, v144, v144
	v_mul_f32_e32 v144, v147, v147
	v_add_f32_e32 v116, v116, v117
	v_mul_f32_e32 v117, v131, v131
	v_mul_f32_e32 v118, v129, v129
	v_fmac_f32_e32 v144, v146, v146
	v_fmac_f32_e32 v117, v130, v130
	v_fmac_f32_e32 v118, v128, v128
	v_add_f32_e32 v143, v143, v144
	v_add_f32_e32 v117, v117, v118
	v_add_f32_e32 v142, v142, v143
	v_add_f32_e32 v116, v116, v117
	v_add_f32_e32 v116, v142, v116
	ds_bpermute_b32 v117, v184, v116
	v_cvt_pk_bf16_f32 v118, v120, v121
	v_cvt_pk_bf16_f32 v119, v122, v123
	v_cvt_pk_bf16_f32 v120, v130, v131
	v_cvt_pk_bf16_f32 v121, v128, v129
	s_waitcnt lgkmcnt(0)
	v_add_f32_e32 v116, v116, v117
	ds_bpermute_b32 v117, v158, v116
	flat_store_dwordx4 v[140:141], v[118:121] offset:256
	s_and_saveexec_b64 s[30:31], s[40:41]
	s_cbranch_execz .LBB0_721
	v_lshlrev_b64 v[118:119], 6, v[230:231]
	v_lshl_add_u64 v[118:119], s[62:63], 0, v[118:119]
	v_lshl_add_u64 v[118:119], s[92:93], 2, v[118:119]
	s_lshl_b32 s58, s53, 2
	v_lshl_add_u64 v[118:119], v[118:119], 0, s[58:59]
	s_waitcnt lgkmcnt(0)
	v_add_f32_e32 v116, v116, v117
	flat_store_dword v[118:119], v116
; __device__ __forceinline__ u32x4 pack8(f32x4 v0, f32x4 v1) { u32x4 w; w.x = pk2(v0[0], v0[1]); w.y = pk2(v0[2], v0[3]); w.z = pk2(v1[0], v1[1]); w.w = pk2(v1[2], v1[3]); return w; }
;     __device__ __forceinline__ void operator()(const f32x4 (&acc)[2][2][4][2], const Unit& u, int wr, int wc, int fr, int fq) const {
;     ...
;         for (int ai = 0; ai < 2; ++ai)
; #pragma unroll
;             for (int m = 0; m < 4; ++m) {
;                 const int row = row0 + ai * 128 + m * 16; const size_t off = (size_t)row * DM + col0; float ss = 0.f;
; #pragma unroll
;                 for (int bj = 0; bj < 2; ++bj) {
;                     f32x4 b0, b1;
;                     if (base32) { b0 = __builtin_nontemporal_load((const f32x4*)(base32 + off + bj * 128)); b1 = __builtin_nontemporal_load((const f32x4*)(base32 + off + bj * 128 + 4)); }
;                     else { const u32x4 w = bw[ai][m][bj]; b0 = (f32x4){bflo(w.x), bfhi(w.x), bflo(w.y), bfhi(w.y)}; b1 = (f32x4){bflo(w.z), bfhi(w.z), bflo(w.w), bfhi(w.w)}; }
;                     const f32x4 x0 = b0 + acc[ai][bj][m][0], x1 = b1 + acc[ai][bj][m][1];
;                     if (out32) { __builtin_nontemporal_store(x0, (f32x4*)(out32 + off + bj * 128)); __builtin_nontemporal_store(x1, (f32x4*)(out32 + off + bj * 128 + 4)); }
;                     else *(u32x4*)(XN + off + bj * 128) = pack8(x0, x1);
;                     ss += ((x0[0] * x0[0] + x0[1] * x0[1]) + (x0[2] * x0[2] + x0[3] * x0[3])) + ((x1[0] * x1[0] + x1[1] * x1[1]) + (x1[2] * x1[2] + x1[3] * x1[3]));
;                 }
;                 ss += __shfl_xor(ss, 16); ss += __shfl_xor(ss, 32);
;                 if (fq == 0) part[(size_t)row * 16 + u.pn * 4 + wc] = ss;
;             }
.LBB0_721:
	s_or_b64 exec, exec, s[30:31]
	s_waitcnt lgkmcnt(0)
	v_lshlrev_b64 v[116:117], 10, v[228:229]
	v_lshl_add_u64 v[130:131], v[116:117], 0, v[224:225]
	s_and_b64 vcc, exec, s[44:45]
	v_lshl_add_u64 v[128:129], v[130:131], 2, s[20:21]
	s_cbranch_vccnz .LBB0_776
	global_load_dwordx4 v[120:123], v[128:129], off offset:16 nt
	global_load_dwordx4 v[116:119], v[128:129], off nt
	s_waitcnt vmcnt(0)
	s_cbranch_execnz .LBB0_724
.LBB0_723:
	s_nop 0
	v_lshlrev_b32_e32 v116, 16, v172
	v_and_b32_e32 v117, 0xffff0000, v172
	v_lshlrev_b32_e32 v118, 16, v173
	v_and_b32_e32 v119, 0xffff0000, v173
	v_lshlrev_b32_e32 v120, 16, v174
	v_and_b32_e32 v121, 0xffff0000, v174
	v_lshlrev_b32_e32 v122, 16, v175
	v_and_b32_e32 v123, 0xffff0000, v175
.LBB0_724:
	v_pk_add_f32 v[118:119], v[110:111], v[118:119]
	v_pk_add_f32 v[132:133], v[108:109], v[116:117]
	v_pk_add_f32 v[122:123], v[106:107], v[122:123]
	v_pk_add_f32 v[120:121], v[104:105], v[120:121]
	v_cvt_pk_bf16_f32 v104, v132, v133
	v_cvt_pk_bf16_f32 v105, v118, v119
	v_cvt_pk_bf16_f32 v106, v120, v121
	v_cvt_pk_bf16_f32 v107, v122, v123
	v_lshl_add_u64 v[116:117], v[130:131], 1, s[54:55]
	s_and_b64 vcc, exec, s[44:45]
	flat_store_dwordx4 v[116:117], v[104:107]
	s_cbranch_vccnz .LBB0_777
	global_load_dwordx4 v[108:111], v[128:129], off offset:528 nt
	global_load_dwordx4 v[104:107], v[128:129], off offset:512 nt
	s_waitcnt vmcnt(0)
	s_cbranch_execnz .LBB0_727
.LBB0_726:
	s_nop 0
	v_lshlrev_b32_e32 v104, 16, v168
	v_and_b32_e32 v105, 0xffff0000, v168
	v_lshlrev_b32_e32 v106, 16, v169
	v_and_b32_e32 v107, 0xffff0000, v169
	v_lshlrev_b32_e32 v108, 16, v170
	v_and_b32_e32 v109, 0xffff0000, v170
	v_lshlrev_b32_e32 v110, 16, v171
	v_and_b32_e32 v111, 0xffff0000, v171
.LBB0_727:
	v_mul_f32_e32 v128, v133, v133
	v_mul_f32_e32 v119, v119, v119
	v_pk_add_f32 v[98:99], v[98:99], v[106:107]
	v_pk_add_f32 v[96:97], v[96:97], v[104:105]
	v_fmac_f32_e32 v128, v132, v132
	v_fmac_f32_e32 v119, v118, v118
	v_pk_add_f32 v[106:107], v[92:93], v[108:109]
	v_mul_f32_e32 v92, v97, v97
	v_mul_f32_e32 v93, v99, v99
	v_add_f32_e32 v118, v128, v119
	v_mul_f32_e32 v119, v121, v121
	v_pk_add_f32 v[104:105], v[94:95], v[110:111]
	v_fmac_f32_e32 v92, v96, v96
	v_fmac_f32_e32 v93, v98, v98
	v_fmac_f32_e32 v119, v120, v120
	v_mul_f32_e32 v120, v123, v123
	v_add_f32_e32 v92, v92, v93
	v_mul_f32_e32 v93, v107, v107
	v_mul_f32_e32 v94, v105, v105
	v_fmac_f32_e32 v120, v122, v122
	v_fmac_f32_e32 v93, v106, v106
	v_fmac_f32_e32 v94, v104, v104
	v_add_f32_e32 v119, v119, v120
	v_add_f32_e32 v93, v93, v94
	v_add_f32_e32 v118, v118, v119
	v_add_f32_e32 v92, v92, v93
	v_add_f32_e32 v92, v118, v92
	ds_bpermute_b32 v93, v184, v92
	v_cvt_pk_bf16_f32 v94, v96, v97
	v_cvt_pk_bf16_f32 v95, v98, v99
	v_cvt_pk_bf16_f32 v96, v106, v107
	v_cvt_pk_bf16_f32 v97, v104, v105
	s_waitcnt lgkmcnt(0)
	v_add_f32_e32 v92, v92, v93
	ds_bpermute_b32 v93, v158, v92
	flat_store_dwordx4 v[116:117], v[94:97] offset:256
	s_and_saveexec_b64 s[30:31], s[40:41]
	s_cbranch_execz .LBB0_729
	v_lshlrev_b64 v[94:95], 6, v[228:229]
	v_lshl_add_u64 v[94:95], s[62:63], 0, v[94:95]
	v_lshl_add_u64 v[94:95], s[92:93], 2, v[94:95]
	s_lshl_b32 s58, s53, 2
	v_lshl_add_u64 v[94:95], v[94:95], 0, s[58:59]
	s_waitcnt lgkmcnt(0)
	v_add_f32_e32 v92, v92, v93
	flat_store_dword v[94:95], v92
.LBB0_729:
	s_or_b64 exec, exec, s[30:31]
	s_waitcnt lgkmcnt(0)
	v_lshlrev_b64 v[92:93], 10, v[226:227]
	v_lshl_add_u64 v[106:107], v[92:93], 0, v[224:225]
	s_and_b64 vcc, exec, s[44:45]
	v_lshl_add_u64 v[104:105], v[106:107], 2, s[20:21]
	s_cbranch_vccnz .LBB0_778
	global_load_dwordx4 v[96:99], v[104:105], off offset:16 nt
	global_load_dwordx4 v[92:95], v[104:105], off nt
	s_waitcnt vmcnt(0)
	s_cbranch_execnz .LBB0_732
.LBB0_731:
	s_nop 0
	v_lshlrev_b32_e32 v92, 16, v164
	v_and_b32_e32 v93, 0xffff0000, v164
	v_lshlrev_b32_e32 v94, 16, v165
	v_and_b32_e32 v95, 0xffff0000, v165
	v_lshlrev_b32_e32 v96, 16, v166
	v_and_b32_e32 v97, 0xffff0000, v166
	v_lshlrev_b32_e32 v98, 16, v167
	v_and_b32_e32 v99, 0xffff0000, v167
.LBB0_732:
	v_pk_add_f32 v[94:95], v[86:87], v[94:95]
	v_pk_add_f32 v[108:109], v[84:85], v[92:93]
	v_pk_add_f32 v[98:99], v[82:83], v[98:99]
	v_pk_add_f32 v[96:97], v[80:81], v[96:97]
	v_cvt_pk_bf16_f32 v80, v108, v109
	v_cvt_pk_bf16_f32 v81, v94, v95
	v_cvt_pk_bf16_f32 v82, v96, v97
	v_cvt_pk_bf16_f32 v83, v98, v99
	v_lshl_add_u64 v[92:93], v[106:107], 1, s[54:55]
	s_and_b64 vcc, exec, s[44:45]
	flat_store_dwordx4 v[92:93], v[80:83]
	s_cbranch_vccnz .LBB0_779
	global_load_dwordx4 v[84:87], v[104:105], off offset:528 nt
	global_load_dwordx4 v[80:83], v[104:105], off offset:512 nt
	s_waitcnt vmcnt(0)
	s_cbranch_execnz .LBB0_735
.LBB0_734:
	s_nop 0
	v_lshlrev_b32_e32 v80, 16, v160
	v_and_b32_e32 v81, 0xffff0000, v160
	v_lshlrev_b32_e32 v82, 16, v161
	v_and_b32_e32 v83, 0xffff0000, v161
	v_lshlrev_b32_e32 v84, 16, v162
	v_and_b32_e32 v85, 0xffff0000, v162
	v_lshlrev_b32_e32 v86, 16, v163
	v_and_b32_e32 v87, 0xffff0000, v163
; __device__ __forceinline__ u32x4 pack8(f32x4 v0, f32x4 v1) { u32x4 w; w.x = pk2(v0[0], v0[1]); w.y = pk2(v0[2], v0[3]); w.z = pk2(v1[0], v1[1]); w.w = pk2(v1[2], v1[3]); return w; }
;     __device__ __forceinline__ void operator()(const f32x4 (&acc)[2][2][4][2], const Unit& u, int wr, int wc, int fr, int fq) const {
;     ...
;         for (int ai = 0; ai < 2; ++ai)
; #pragma unroll
;             for (int m = 0; m < 4; ++m) {
;                 const int row = row0 + ai * 128 + m * 16; const size_t off = (size_t)row * DM + col0; float ss = 0.f;
; #pragma unroll
;                 for (int bj = 0; bj < 2; ++bj) {
;                     f32x4 b0, b1;
;                     if (base32) { b0 = __builtin_nontemporal_load((const f32x4*)(base32 + off + bj * 128)); b1 = __builtin_nontemporal_load((const f32x4*)(base32 + off + bj * 128 + 4)); }
;                     else { const u32x4 w = bw[ai][m][bj]; b0 = (f32x4){bflo(w.x), bfhi(w.x), bflo(w.y), bfhi(w.y)}; b1 = (f32x4){bflo(w.z), bfhi(w.z), bflo(w.w), bfhi(w.w)}; }
;                     const f32x4 x0 = b0 + acc[ai][bj][m][0], x1 = b1 + acc[ai][bj][m][1];
;                     if (out32) { __builtin_nontemporal_store(x0, (f32x4*)(out32 + off + bj * 128)); __builtin_nontemporal_store(x1, (f32x4*)(out32 + off + bj * 128 + 4)); }
;                     else *(u32x4*)(XN + off + bj * 128) = pack8(x0, x1);
;                     ss += ((x0[0] * x0[0] + x0[1] * x0[1]) + (x0[2] * x0[2] + x0[3] * x0[3])) + ((x1[0] * x1[0] + x1[1] * x1[1]) + (x1[2] * x1[2] + x1[3] * x1[3]));
;                 }
;                 ss += __shfl_xor(ss, 16); ss += __shfl_xor(ss, 32);
;                 if (fq == 0) part[(size_t)row * 16 + u.pn * 4 + wc] = ss;
;             }
.LBB0_735:
	v_mul_f32_e32 v104, v109, v109
	v_mul_f32_e32 v95, v95, v95
	v_pk_add_f32 v[74:75], v[74:75], v[82:83]
	v_pk_add_f32 v[72:73], v[72:73], v[80:81]
	v_fmac_f32_e32 v104, v108, v108
	v_fmac_f32_e32 v95, v94, v94
	v_pk_add_f32 v[82:83], v[68:69], v[84:85]
	v_mul_f32_e32 v68, v73, v73
	v_mul_f32_e32 v69, v75, v75
	v_add_f32_e32 v94, v104, v95
	v_mul_f32_e32 v95, v97, v97
	v_pk_add_f32 v[80:81], v[70:71], v[86:87]
	v_fmac_f32_e32 v68, v72, v72
	v_fmac_f32_e32 v69, v74, v74
	v_fmac_f32_e32 v95, v96, v96
	v_mul_f32_e32 v96, v99, v99
	v_add_f32_e32 v68, v68, v69
	v_mul_f32_e32 v69, v83, v83
	v_mul_f32_e32 v70, v81, v81
	v_fmac_f32_e32 v96, v98, v98
	v_fmac_f32_e32 v69, v82, v82
	v_fmac_f32_e32 v70, v80, v80
	v_add_f32_e32 v95, v95, v96
	v_add_f32_e32 v69, v69, v70
	v_add_f32_e32 v94, v94, v95
	v_add_f32_e32 v68, v68, v69
	v_add_f32_e32 v68, v94, v68
	ds_bpermute_b32 v69, v184, v68
	v_cvt_pk_bf16_f32 v70, v72, v73
	v_cvt_pk_bf16_f32 v71, v74, v75
	v_cvt_pk_bf16_f32 v72, v82, v83
	v_cvt_pk_bf16_f32 v73, v80, v81
	s_waitcnt lgkmcnt(0)
	v_add_f32_e32 v68, v68, v69
	ds_bpermute_b32 v69, v158, v68
	flat_store_dwordx4 v[92:93], v[70:73] offset:256
	s_and_saveexec_b64 s[30:31], s[40:41]
	s_cbranch_execz .LBB0_737
	v_lshlrev_b64 v[70:71], 6, v[226:227]
	v_lshl_add_u64 v[70:71], s[62:63], 0, v[70:71]
	v_lshl_add_u64 v[70:71], s[92:93], 2, v[70:71]
	s_lshl_b32 s58, s53, 2
	v_lshl_add_u64 v[70:71], v[70:71], 0, s[58:59]
	s_waitcnt lgkmcnt(0)
	v_add_f32_e32 v68, v68, v69
	flat_store_dword v[70:71], v68
.LBB0_737:
	s_or_b64 exec, exec, s[30:31]
	v_add_u32_e32 v80, 0x80, v222
	v_ashrrev_i32_e32 v81, 31, v80
	s_waitcnt lgkmcnt(0)
	v_lshlrev_b64 v[68:69], 10, v[80:81]
	v_lshl_add_u64 v[84:85], v[68:69], 0, v[224:225]
	s_and_b64 vcc, exec, s[44:45]
	v_lshl_add_u64 v[82:83], v[84:85], 2, s[20:21]
	s_cbranch_vccnz .LBB0_780
	global_load_dwordx4 v[72:75], v[82:83], off offset:16 nt
	global_load_dwordx4 v[68:71], v[82:83], off nt
	s_waitcnt vmcnt(0)
	s_cbranch_execnz .LBB0_740
.LBB0_739:
	s_nop 0
	v_lshlrev_b32_e32 v68, 16, v148
	v_and_b32_e32 v69, 0xffff0000, v148
	v_lshlrev_b32_e32 v70, 16, v149
	v_and_b32_e32 v71, 0xffff0000, v149
	v_lshlrev_b32_e32 v72, 16, v150
	v_and_b32_e32 v73, 0xffff0000, v150
	v_lshlrev_b32_e32 v74, 16, v151
	v_and_b32_e32 v75, 0xffff0000, v151
.LBB0_740:
	v_pk_add_f32 v[70:71], v[62:63], v[70:71]
	v_pk_add_f32 v[86:87], v[60:61], v[68:69]
	v_pk_add_f32 v[74:75], v[58:59], v[74:75]
	v_pk_add_f32 v[72:73], v[56:57], v[72:73]
	v_cvt_pk_bf16_f32 v56, v86, v87
	v_cvt_pk_bf16_f32 v57, v70, v71
	v_cvt_pk_bf16_f32 v58, v72, v73
	v_cvt_pk_bf16_f32 v59, v74, v75
	v_lshl_add_u64 v[68:69], v[84:85], 1, s[54:55]
	s_and_b64 vcc, exec, s[44:45]
	flat_store_dwordx4 v[68:69], v[56:59]
	s_cbranch_vccnz .LBB0_781
	global_load_dwordx4 v[60:63], v[82:83], off offset:528 nt
	global_load_dwordx4 v[56:59], v[82:83], off offset:512 nt
	s_waitcnt vmcnt(0)
	s_cbranch_execnz .LBB0_743
.LBB0_742:
	s_nop 0
	v_lshlrev_b32_e32 v56, 16, v136
	v_and_b32_e32 v57, 0xffff0000, v136
	v_lshlrev_b32_e32 v58, 16, v137
	v_and_b32_e32 v59, 0xffff0000, v137
	v_lshlrev_b32_e32 v60, 16, v138
	v_and_b32_e32 v61, 0xffff0000, v138
	v_lshlrev_b32_e32 v62, 16, v139
	v_and_b32_e32 v63, 0xffff0000, v139
.LBB0_743:
	v_mul_f32_e32 v82, v87, v87
	v_mul_f32_e32 v71, v71, v71
	v_pk_add_f32 v[54:55], v[54:55], v[58:59]
	v_pk_add_f32 v[52:53], v[52:53], v[56:57]
	v_fmac_f32_e32 v82, v86, v86
	v_fmac_f32_e32 v71, v70, v70
	v_pk_add_f32 v[58:59], v[48:49], v[60:61]
	v_mul_f32_e32 v48, v53, v53
	v_mul_f32_e32 v49, v55, v55
	v_add_f32_e32 v70, v82, v71
	v_mul_f32_e32 v71, v73, v73
	v_pk_add_f32 v[56:57], v[50:51], v[62:63]
	v_fmac_f32_e32 v48, v52, v52
	v_fmac_f32_e32 v49, v54, v54
	v_fmac_f32_e32 v71, v72, v72
	v_mul_f32_e32 v72, v75, v75
	v_add_f32_e32 v48, v48, v49
	v_mul_f32_e32 v49, v59, v59
	v_mul_f32_e32 v50, v57, v57
	v_fmac_f32_e32 v72, v74, v74
	v_fmac_f32_e32 v49, v58, v58
	v_fmac_f32_e32 v50, v56, v56
	v_add_f32_e32 v71, v71, v72
	v_add_f32_e32 v49, v49, v50
	v_add_f32_e32 v70, v70, v71
	v_add_f32_e32 v48, v48, v49
	v_add_f32_e32 v48, v70, v48
	ds_bpermute_b32 v49, v184, v48
	v_cvt_pk_bf16_f32 v50, v52, v53
	v_cvt_pk_bf16_f32 v51, v54, v55
	v_cvt_pk_bf16_f32 v52, v58, v59
	v_cvt_pk_bf16_f32 v53, v56, v57
	s_waitcnt lgkmcnt(0)
	v_add_f32_e32 v48, v48, v49
	ds_bpermute_b32 v49, v158, v48
	flat_store_dwordx4 v[68:69], v[50:53] offset:256
	s_and_saveexec_b64 s[30:31], s[40:41]
	s_cbranch_execz .LBB0_745
	v_lshlrev_b64 v[50:51], 6, v[80:81]
	v_lshl_add_u64 v[50:51], s[62:63], 0, v[50:51]
	v_lshl_add_u64 v[50:51], s[92:93], 2, v[50:51]
	s_lshl_b32 s58, s53, 2
	v_lshl_add_u64 v[50:51], v[50:51], 0, s[58:59]
	s_waitcnt lgkmcnt(0)
	v_add_f32_e32 v48, v48, v49
	flat_store_dword v[50:51], v48
.LBB0_745:
	s_or_b64 exec, exec, s[30:31]
	v_add_u32_e32 v56, 0x90, v222
	v_ashrrev_i32_e32 v57, 31, v56
	s_waitcnt lgkmcnt(0)
	v_lshlrev_b64 v[48:49], 10, v[56:57]
	v_lshl_add_u64 v[60:61], v[48:49], 0, v[224:225]
	s_and_b64 vcc, exec, s[44:45]
	v_lshl_add_u64 v[58:59], v[60:61], 2, s[20:21]
	s_cbranch_vccnz .LBB0_782
	global_load_dwordx4 v[52:55], v[58:59], off offset:16 nt
	global_load_dwordx4 v[48:51], v[58:59], off nt
	s_waitcnt vmcnt(0)
	s_cbranch_execnz .LBB0_748
.LBB0_747:
	s_nop 0
	v_lshlrev_b32_e32 v48, 16, v124
	v_and_b32_e32 v49, 0xffff0000, v124
	v_lshlrev_b32_e32 v50, 16, v125
	v_and_b32_e32 v51, 0xffff0000, v125
	v_lshlrev_b32_e32 v52, 16, v126
	v_and_b32_e32 v53, 0xffff0000, v126
	v_lshlrev_b32_e32 v54, 16, v127
	v_and_b32_e32 v55, 0xffff0000, v127
; __device__ __forceinline__ u32x4 pack8(f32x4 v0, f32x4 v1) { u32x4 w; w.x = pk2(v0[0], v0[1]); w.y = pk2(v0[2], v0[3]); w.z = pk2(v1[0], v1[1]); w.w = pk2(v1[2], v1[3]); return w; }
;     __device__ __forceinline__ void operator()(const f32x4 (&acc)[2][2][4][2], const Unit& u, int wr, int wc, int fr, int fq) const {
;     ...
;         for (int ai = 0; ai < 2; ++ai)
; #pragma unroll
;             for (int m = 0; m < 4; ++m) {
;                 const int row = row0 + ai * 128 + m * 16; const size_t off = (size_t)row * DM + col0; float ss = 0.f;
; #pragma unroll
;                 for (int bj = 0; bj < 2; ++bj) {
;                     f32x4 b0, b1;
;                     if (base32) { b0 = __builtin_nontemporal_load((const f32x4*)(base32 + off + bj * 128)); b1 = __builtin_nontemporal_load((const f32x4*)(base32 + off + bj * 128 + 4)); }
;                     else { const u32x4 w = bw[ai][m][bj]; b0 = (f32x4){bflo(w.x), bfhi(w.x), bflo(w.y), bfhi(w.y)}; b1 = (f32x4){bflo(w.z), bfhi(w.z), bflo(w.w), bfhi(w.w)}; }
;                     const f32x4 x0 = b0 + acc[ai][bj][m][0], x1 = b1 + acc[ai][bj][m][1];
;                     if (out32) { __builtin_nontemporal_store(x0, (f32x4*)(out32 + off + bj * 128)); __builtin_nontemporal_store(x1, (f32x4*)(out32 + off + bj * 128 + 4)); }
;                     else *(u32x4*)(XN + off + bj * 128) = pack8(x0, x1);
;                     ss += ((x0[0] * x0[0] + x0[1] * x0[1]) + (x0[2] * x0[2] + x0[3] * x0[3])) + ((x1[0] * x1[0] + x1[1] * x1[1]) + (x1[2] * x1[2] + x1[3] * x1[3]));
;                 }
;                 ss += __shfl_xor(ss, 16); ss += __shfl_xor(ss, 32);
;                 if (fq == 0) part[(size_t)row * 16 + u.pn * 4 + wc] = ss;
;             }
.LBB0_748:
	v_pk_add_f32 v[50:51], v[46:47], v[50:51]
	v_pk_add_f32 v[62:63], v[44:45], v[48:49]
	v_pk_add_f32 v[54:55], v[42:43], v[54:55]
	v_pk_add_f32 v[52:53], v[40:41], v[52:53]
	v_cvt_pk_bf16_f32 v40, v62, v63
	v_cvt_pk_bf16_f32 v41, v50, v51
	v_cvt_pk_bf16_f32 v42, v52, v53
	v_cvt_pk_bf16_f32 v43, v54, v55
	v_lshl_add_u64 v[48:49], v[60:61], 1, s[54:55]
	s_and_b64 vcc, exec, s[44:45]
	flat_store_dwordx4 v[48:49], v[40:43]
	s_cbranch_vccnz .LBB0_783
	global_load_dwordx4 v[44:47], v[58:59], off offset:528 nt
	global_load_dwordx4 v[40:43], v[58:59], off offset:512 nt
	s_waitcnt vmcnt(0)
	s_cbranch_execnz .LBB0_751
.LBB0_750:
	s_nop 0
	v_lshlrev_b32_e32 v40, 16, v112
	v_and_b32_e32 v41, 0xffff0000, v112
	v_lshlrev_b32_e32 v42, 16, v113
	v_and_b32_e32 v43, 0xffff0000, v113
	v_lshlrev_b32_e32 v44, 16, v114
	v_and_b32_e32 v45, 0xffff0000, v114
	v_lshlrev_b32_e32 v46, 16, v115
	v_and_b32_e32 v47, 0xffff0000, v115
.LBB0_751:
	v_mul_f32_e32 v58, v63, v63
	v_mul_f32_e32 v51, v51, v51
	v_pk_add_f32 v[38:39], v[38:39], v[42:43]
	v_pk_add_f32 v[36:37], v[36:37], v[40:41]
	v_fmac_f32_e32 v58, v62, v62
	v_fmac_f32_e32 v51, v50, v50
	v_pk_add_f32 v[42:43], v[32:33], v[44:45]
	v_mul_f32_e32 v32, v37, v37
	v_mul_f32_e32 v33, v39, v39
	v_add_f32_e32 v50, v58, v51
	v_mul_f32_e32 v51, v53, v53
	v_pk_add_f32 v[40:41], v[34:35], v[46:47]
	v_fmac_f32_e32 v32, v36, v36
	v_fmac_f32_e32 v33, v38, v38
	v_fmac_f32_e32 v51, v52, v52
	v_mul_f32_e32 v52, v55, v55
	v_add_f32_e32 v32, v32, v33
	v_mul_f32_e32 v33, v43, v43
	v_mul_f32_e32 v34, v41, v41
	v_fmac_f32_e32 v52, v54, v54
	v_fmac_f32_e32 v33, v42, v42
	v_fmac_f32_e32 v34, v40, v40
	v_add_f32_e32 v51, v51, v52
	v_add_f32_e32 v33, v33, v34
	v_add_f32_e32 v50, v50, v51
	v_add_f32_e32 v32, v32, v33
	v_add_f32_e32 v32, v50, v32
	ds_bpermute_b32 v33, v184, v32
	v_cvt_pk_bf16_f32 v34, v36, v37
	v_cvt_pk_bf16_f32 v35, v38, v39
	v_cvt_pk_bf16_f32 v36, v42, v43
	v_cvt_pk_bf16_f32 v37, v40, v41
	s_waitcnt lgkmcnt(0)
	v_add_f32_e32 v32, v32, v33
	ds_bpermute_b32 v33, v158, v32
	flat_store_dwordx4 v[48:49], v[34:37] offset:256
	s_and_saveexec_b64 s[30:31], s[40:41]
	s_cbranch_execz .LBB0_753
	v_lshlrev_b64 v[34:35], 6, v[56:57]
	v_lshl_add_u64 v[34:35], s[62:63], 0, v[34:35]
	v_lshl_add_u64 v[34:35], s[92:93], 2, v[34:35]
	s_lshl_b32 s58, s53, 2
	v_lshl_add_u64 v[34:35], v[34:35], 0, s[58:59]
	s_waitcnt lgkmcnt(0)
	v_add_f32_e32 v32, v32, v33
	flat_store_dword v[34:35], v32
.LBB0_753:
	s_or_b64 exec, exec, s[30:31]
	v_add_u32_e32 v40, 0xa0, v222
	v_ashrrev_i32_e32 v41, 31, v40
	s_waitcnt lgkmcnt(0)
	v_lshlrev_b64 v[32:33], 10, v[40:41]
	v_lshl_add_u64 v[44:45], v[32:33], 0, v[224:225]
	s_and_b64 vcc, exec, s[44:45]
	v_lshl_add_u64 v[42:43], v[44:45], 2, s[20:21]
	s_cbranch_vccnz .LBB0_784
	global_load_dwordx4 v[36:39], v[42:43], off offset:16 nt
	global_load_dwordx4 v[32:35], v[42:43], off nt
	s_waitcnt vmcnt(0)
	s_cbranch_execnz .LBB0_756
.LBB0_755:
	s_nop 0
	v_lshlrev_b32_e32 v32, 16, v100
	v_and_b32_e32 v33, 0xffff0000, v100
	v_lshlrev_b32_e32 v34, 16, v101
	v_and_b32_e32 v35, 0xffff0000, v101
	v_lshlrev_b32_e32 v36, 16, v102
	v_and_b32_e32 v37, 0xffff0000, v102
	v_lshlrev_b32_e32 v38, 16, v103
	v_and_b32_e32 v39, 0xffff0000, v103
.LBB0_756:
	v_pk_add_f32 v[34:35], v[30:31], v[34:35]
	v_pk_add_f32 v[46:47], v[28:29], v[32:33]
	v_pk_add_f32 v[38:39], v[26:27], v[38:39]
	v_pk_add_f32 v[36:37], v[24:25], v[36:37]
	v_cvt_pk_bf16_f32 v24, v46, v47
	v_cvt_pk_bf16_f32 v25, v34, v35
	v_cvt_pk_bf16_f32 v26, v36, v37
	v_cvt_pk_bf16_f32 v27, v38, v39
	v_lshl_add_u64 v[32:33], v[44:45], 1, s[54:55]
	s_and_b64 vcc, exec, s[44:45]
	flat_store_dwordx4 v[32:33], v[24:27]
	s_cbranch_vccnz .LBB0_785
	global_load_dwordx4 v[28:31], v[42:43], off offset:528 nt
	global_load_dwordx4 v[24:27], v[42:43], off offset:512 nt
	s_waitcnt vmcnt(0)
	s_cbranch_execnz .LBB0_759
.LBB0_758:
	s_nop 0
	v_lshlrev_b32_e32 v24, 16, v88
	v_and_b32_e32 v25, 0xffff0000, v88
	v_lshlrev_b32_e32 v26, 16, v89
	v_and_b32_e32 v27, 0xffff0000, v89
	v_lshlrev_b32_e32 v28, 16, v90
	v_and_b32_e32 v29, 0xffff0000, v90
	v_lshlrev_b32_e32 v30, 16, v91
	v_and_b32_e32 v31, 0xffff0000, v91
; __device__ __forceinline__ u32x4 pack8(f32x4 v0, f32x4 v1) { u32x4 w; w.x = pk2(v0[0], v0[1]); w.y = pk2(v0[2], v0[3]); w.z = pk2(v1[0], v1[1]); w.w = pk2(v1[2], v1[3]); return w; }
;     __device__ __forceinline__ void operator()(const f32x4 (&acc)[2][2][4][2], const Unit& u, int wr, int wc, int fr, int fq) const {
;     ...
;         for (int ai = 0; ai < 2; ++ai)
; #pragma unroll
;             for (int m = 0; m < 4; ++m) {
;                 const int row = row0 + ai * 128 + m * 16; const size_t off = (size_t)row * DM + col0; float ss = 0.f;
; #pragma unroll
;                 for (int bj = 0; bj < 2; ++bj) {
;                     f32x4 b0, b1;
;                     if (base32) { b0 = __builtin_nontemporal_load((const f32x4*)(base32 + off + bj * 128)); b1 = __builtin_nontemporal_load((const f32x4*)(base32 + off + bj * 128 + 4)); }
;                     else { const u32x4 w = bw[ai][m][bj]; b0 = (f32x4){bflo(w.x), bfhi(w.x), bflo(w.y), bfhi(w.y)}; b1 = (f32x4){bflo(w.z), bfhi(w.z), bflo(w.w), bfhi(w.w)}; }
;                     const f32x4 x0 = b0 + acc[ai][bj][m][0], x1 = b1 + acc[ai][bj][m][1];
;                     if (out32) { __builtin_nontemporal_store(x0, (f32x4*)(out32 + off + bj * 128)); __builtin_nontemporal_store(x1, (f32x4*)(out32 + off + bj * 128 + 4)); }
;                     else *(u32x4*)(XN + off + bj * 128) = pack8(x0, x1);
;                     ss += ((x0[0] * x0[0] + x0[1] * x0[1]) + (x0[2] * x0[2] + x0[3] * x0[3])) + ((x1[0] * x1[0] + x1[1] * x1[1]) + (x1[2] * x1[2] + x1[3] * x1[3]));
;                 }
;                 ss += __shfl_xor(ss, 16); ss += __shfl_xor(ss, 32);
;                 if (fq == 0) part[(size_t)row * 16 + u.pn * 4 + wc] = ss;
;             }
.LBB0_759:
	v_mul_f32_e32 v42, v47, v47
	v_mul_f32_e32 v35, v35, v35
	v_pk_add_f32 v[22:23], v[22:23], v[26:27]
	v_pk_add_f32 v[20:21], v[20:21], v[24:25]
	v_fmac_f32_e32 v42, v46, v46
	v_fmac_f32_e32 v35, v34, v34
	v_pk_add_f32 v[26:27], v[16:17], v[28:29]
	v_mul_f32_e32 v16, v21, v21
	v_mul_f32_e32 v17, v23, v23
	v_add_f32_e32 v34, v42, v35
	v_mul_f32_e32 v35, v37, v37
	v_pk_add_f32 v[24:25], v[18:19], v[30:31]
	v_fmac_f32_e32 v16, v20, v20
	v_fmac_f32_e32 v17, v22, v22
	v_fmac_f32_e32 v35, v36, v36
	v_mul_f32_e32 v36, v39, v39
	v_add_f32_e32 v16, v16, v17
	v_mul_f32_e32 v17, v27, v27
	v_mul_f32_e32 v18, v25, v25
	v_fmac_f32_e32 v36, v38, v38
	v_fmac_f32_e32 v17, v26, v26
	v_fmac_f32_e32 v18, v24, v24
	v_add_f32_e32 v35, v35, v36
	v_add_f32_e32 v17, v17, v18
	v_add_f32_e32 v34, v34, v35
	v_add_f32_e32 v16, v16, v17
	v_add_f32_e32 v16, v34, v16
	ds_bpermute_b32 v17, v184, v16
	v_cvt_pk_bf16_f32 v18, v20, v21
	v_cvt_pk_bf16_f32 v19, v22, v23
	v_cvt_pk_bf16_f32 v20, v26, v27
	v_cvt_pk_bf16_f32 v21, v24, v25
	s_waitcnt lgkmcnt(0)
	v_add_f32_e32 v16, v16, v17
	ds_bpermute_b32 v17, v158, v16
	flat_store_dwordx4 v[32:33], v[18:21] offset:256
	s_and_saveexec_b64 s[30:31], s[40:41]
	s_cbranch_execz .LBB0_761
	v_lshlrev_b64 v[18:19], 6, v[40:41]
	v_lshl_add_u64 v[18:19], s[62:63], 0, v[18:19]
	v_lshl_add_u64 v[18:19], s[92:93], 2, v[18:19]
	s_lshl_b32 s58, s53, 2
	v_lshl_add_u64 v[18:19], v[18:19], 0, s[58:59]
	s_waitcnt lgkmcnt(0)
	v_add_f32_e32 v16, v16, v17
	flat_store_dword v[18:19], v16
.LBB0_761:
	s_or_b64 exec, exec, s[30:31]
	v_add_u32_e32 v24, 0xb0, v222
	v_ashrrev_i32_e32 v25, 31, v24
	s_waitcnt lgkmcnt(0)
	v_lshlrev_b64 v[16:17], 10, v[24:25]
	v_lshl_add_u64 v[28:29], v[16:17], 0, v[224:225]
	s_and_b64 vcc, exec, s[44:45]
	v_lshl_add_u64 v[26:27], v[28:29], 2, s[20:21]
	s_cbranch_vccnz .LBB0_786
	global_load_dwordx4 v[20:23], v[26:27], off offset:16 nt
	global_load_dwordx4 v[16:19], v[26:27], off nt
	s_waitcnt vmcnt(0)
	s_cbranch_execnz .LBB0_764
.LBB0_763:
	s_nop 0
	v_lshlrev_b32_e32 v16, 16, v76
	v_and_b32_e32 v17, 0xffff0000, v76
	v_lshlrev_b32_e32 v18, 16, v77
	v_and_b32_e32 v19, 0xffff0000, v77
	v_lshlrev_b32_e32 v20, 16, v78
	v_and_b32_e32 v21, 0xffff0000, v78
	v_lshlrev_b32_e32 v22, 16, v79
	v_and_b32_e32 v23, 0xffff0000, v79
.LBB0_764:
	v_pk_add_f32 v[18:19], v[14:15], v[18:19]
	v_pk_add_f32 v[30:31], v[12:13], v[16:17]
	v_pk_add_f32 v[22:23], v[10:11], v[22:23]
	v_pk_add_f32 v[20:21], v[8:9], v[20:21]
	v_cvt_pk_bf16_f32 v8, v30, v31
	v_cvt_pk_bf16_f32 v9, v18, v19
	v_cvt_pk_bf16_f32 v10, v20, v21
	v_cvt_pk_bf16_f32 v11, v22, v23
	v_lshl_add_u64 v[16:17], v[28:29], 1, s[54:55]
	s_and_b64 vcc, exec, s[44:45]
	flat_store_dwordx4 v[16:17], v[8:11]
	s_cbranch_vccnz .LBB0_787
	global_load_dwordx4 v[12:15], v[26:27], off offset:528 nt
	global_load_dwordx4 v[8:11], v[26:27], off offset:512 nt
	s_waitcnt vmcnt(0)
	s_cbranch_execnz .LBB0_767
.LBB0_766:
	s_nop 0
	v_lshlrev_b32_e32 v8, 16, v64
	v_and_b32_e32 v9, 0xffff0000, v64
	v_lshlrev_b32_e32 v10, 16, v65
	v_and_b32_e32 v11, 0xffff0000, v65
	v_lshlrev_b32_e32 v12, 16, v66
	v_and_b32_e32 v13, 0xffff0000, v66
	v_lshlrev_b32_e32 v14, 16, v67
	v_and_b32_e32 v15, 0xffff0000, v67
.LBB0_767:
	v_mul_f32_e32 v26, v31, v31
	v_mul_f32_e32 v19, v19, v19
	v_pk_add_f32 v[6:7], v[6:7], v[10:11]
	v_pk_add_f32 v[4:5], v[4:5], v[8:9]
	v_fmac_f32_e32 v26, v30, v30
	v_fmac_f32_e32 v19, v18, v18
	v_pk_add_f32 v[10:11], v[0:1], v[12:13]
	v_mul_f32_e32 v0, v5, v5
	v_mul_f32_e32 v1, v7, v7
	v_add_f32_e32 v18, v26, v19
	v_mul_f32_e32 v19, v21, v21
	v_pk_add_f32 v[8:9], v[2:3], v[14:15]
	v_fmac_f32_e32 v0, v4, v4
	v_fmac_f32_e32 v1, v6, v6
	v_fmac_f32_e32 v19, v20, v20
	v_mul_f32_e32 v20, v23, v23
	v_add_f32_e32 v0, v0, v1
	v_mul_f32_e32 v1, v11, v11
	v_mul_f32_e32 v2, v9, v9
	v_fmac_f32_e32 v20, v22, v22
	v_fmac_f32_e32 v1, v10, v10
	v_fmac_f32_e32 v2, v8, v8
	v_add_f32_e32 v19, v19, v20
	v_add_f32_e32 v1, v1, v2
	v_add_f32_e32 v18, v18, v19
	v_add_f32_e32 v0, v0, v1
	v_add_f32_e32 v0, v18, v0
	ds_bpermute_b32 v1, v184, v0
	v_cvt_pk_bf16_f32 v2, v4, v5
	v_cvt_pk_bf16_f32 v3, v6, v7
	v_cvt_pk_bf16_f32 v4, v10, v11
	v_cvt_pk_bf16_f32 v5, v8, v9
	s_waitcnt lgkmcnt(0)
	v_add_f32_e32 v0, v0, v1
	ds_bpermute_b32 v1, v158, v0
	flat_store_dwordx4 v[16:17], v[2:5] offset:256
	s_and_saveexec_b64 s[30:31], s[40:41]
	s_cbranch_execz .LBB0_769
	v_lshlrev_b64 v[2:3], 6, v[24:25]
	v_lshl_add_u64 v[2:3], s[62:63], 0, v[2:3]
	v_lshl_add_u64 v[2:3], s[92:93], 2, v[2:3]
	s_lshl_b32 s58, s53, 2
	v_lshl_add_u64 v[2:3], v[2:3], 0, s[58:59]
	s_waitcnt lgkmcnt(0)
	v_add_f32_e32 v0, v0, v1
	flat_store_dword v[2:3], v0
